# mlp2 out-projection phase rewritten by hand: 128x256 tile, 3-stage LDS-DMA ring, dwordx4 residual epilogue
# speedup vs baseline: 1.0453x; 1.0453x over previous
; __device__ __forceinline__ int otid() { int t = threadIdx.x; asm volatile("" : "+v"(t)); return t; }
; template <int NI> ...
;     ...
;   const int lane = tid & 63, wid = tid >> 6, wr = wid >> 1, wc = wid & 1;
;   const int lrow = tid >> 2, lch = (tid & 3) * 8;
;   const int l15 = lane & 15, lq = lane >> 4;
;   const bf16_t* pa = A + (size_t)lrow * lda + lch;
;   const bf16_t* pb = B + (size_t)lrow * ldb + lch;
;   const size_t a64 = (size_t)64 * lda, b64 = (size_t)64 * ldb;
;   u32x4 a0[2], a1[2], b0[NB], b1[NB];
;   const int nk = K >> 5;
;   const int klast = K - 32;
;   const int wofs = lrow * GROW + lch;
;   const int raofs = (wr * 64 + l15) * GROW + lq * 8;
;   const int rbofs = 128 * GROW + (wc * (16 * NI) + l15) * GROW + lq * 8;
;     ...
;   G_LOAD(a0, b0, 0);
;   G_LOAD(a1, b1, 32);
;   __syncthreads();
;   G_WRITE(a0, b0, 0);
;   __syncthreads();
; __device__ void phase_proj_res(CParams& p, int l, int tm, int tn, char* smem, const bf16_t* A, int K,
;                                const bf16_t* Bt, int gate_off, float gscale) {
;   const int tid = otid();
;   bf16_t* sA = (bf16_t*)smem;
;   bf16_t* sB = sA + 128 * LDSS;
;   int row0 = tm * 128, col0 = tn * 128;
;   f32x4 acc[4][4];
;   zero_acc<4>(acc);
;   gemm_mainloop<4>(A + (size_t)row0 * K, K, Bt + (size_t)col0 * K, K, K, sA, sB, acc, tid);
.LBB0_1127:
	s_or_b64 exec, exec, s[20:21]
	s_mov_b64 s[20:21], s[34:35]
	s_waitcnt lgkmcnt(0)
	s_barrier
	s_load_dwordx2 s[6:7], s[20:21], 0x128
	s_load_dwordx2 s[22:23], s[20:21], 0x1e0
	s_load_dwordx2 s[24:25], s[20:21], 0x160
	s_load_dwordx2 s[44:45], s[20:21], 0x148
	s_load_dwordx2 s[48:49], s[20:21], 0xf8
	s_waitcnt lgkmcnt(0)
	s_add_u32 s2, s6, s18
	s_addc_u32 s4, s7, s19
	v_readlane_b32 s6, v224, 15
	v_readlane_b32 s7, v224, 16
	s_add_u32 s18, s2, s6
	s_addc_u32 s19, s4, s7
	s_mov_b32 s2, 0
	s_mov_b64 exec, -1
	ds_read_b128 v[236:239], v145 offset:40960
	s_load_dwordx2 s[6:7], s[20:21], 0x1e0
	s_load_dwordx2 s[12:13], s[20:21], 0x128
	s_load_dwordx2 s[22:23], s[20:21], 0xf8
	s_load_dwordx2 s[26:27], s[20:21], 0x160
	v_readlane_b32 s0, v224, 26
	v_readlane_b32 s2, v225, 4
	v_readfirstlane_b32 s4, v147
	v_and_b32_e32 v250, 63, v147
	s_nop 3
	s_lshr_b32 s4, s4, 6
	s_lshl_b32 s8, s4, 11
	s_lshl_b32 s10, s4, 12
	s_and_b32 s40, s2, 7
	s_lshl_b32 s40, s40, 4
	s_lshr_b32 s41, s2, 5
	s_add_u32 s40, s40, s41
	s_lshl_b32 s32, s40, 7
	s_lshr_b32 s41, s2, 3
	s_and_b32 s41, s41, 3
	s_lshl_b32 s28, s41, 8
	v_lshrrev_b32_e32 v251, 2, v250
	v_and_b32_e32 v252, 3, v250
	v_lshrrev_b32_e32 v253, 4, v250
	v_sub_u32_e32 v253, 0, v253
	v_and_b32_e32 v253, 3, v253
	v_xor_b32_e32 v253, v252, v253
	v_lshlrev_b32_e32 v253, 4, v253
	s_lshl_b32 s40, s4, 5
	v_add_u32_e32 v252, s40, v251
	s_mov_b32 s41, 0x2000
	v_mul_lo_u32 v240, v252, s41
	v_add_u32_e32 v240, v240, v253
	v_add_u32_e32 v241, 0x20000, v240
	s_lshl_b32 s40, s4, 6
	v_add_u32_e32 v252, s40, v251
	s_mov_b32 s41, 0x2000
	v_mul_lo_u32 v242, v252, s41
	v_add_u32_e32 v242, v242, v253
	v_add_u32_e32 v243, 0x20000, v242
	v_add_u32_e32 v244, 0x40000, v242
	v_add_u32_e32 v245, 0x60000, v242
	v_and_b32_e32 v251, 15, v250
	v_lshrrev_b32_e32 v252, 2, v251
	v_sub_u32_e32 v252, 0, v252
	v_and_b32_e32 v252, 3, v252
	v_lshrrev_b32_e32 v253, 4, v250
	v_xor_b32_e32 v252, v253, v252
	v_lshlrev_b32_e32 v252, 4, v252
	s_lshr_b32 s40, s4, 1
	s_and_b32 s41, s4, 1
	s_lshl_b32 s52, s40, 6
	s_lshl_b32 s53, s41, 7
	v_add_u32_e32 v246, s52, v251
	v_lshl_add_u32 v246, v246, 6, v252
	v_add_u32_e32 v247, s53, v251
	v_lshl_add_u32 v247, v247, 6, v252
	v_add_u32_e32 v247, 0x2000, v247
	v_lshl_add_u32 v249, v253, 2, s53
	v_lshlrev_b32_e32 v249, 2, v249
	v_add_u32_e32 v248, s52, v251
	v_lshl_add_u32 v248, v248, 12, v249
	s_waitcnt lgkmcnt(0)
	s_mul_i32 s40, s32, 0x2000
	s_add_u32 s16, s6, s40
	s_addc_u32 s17, s7, 0
	s_mul_i32 s40, s0, 0x800000
	s_mul_i32 s41, s28, 0x2000
	s_add_u32 s40, s40, s41
	s_add_u32 s18, s12, s40
	s_addc_u32 s19, s13, 0
	s_barrier
	s_add_u32 m0, s8, 0x0
	s_nop 0
	global_load_lds_dwordx4 v240, s[16:17]
	s_add_u32 m0, s8, 0x400
	s_nop 0
	global_load_lds_dwordx4 v241, s[16:17]
	s_add_u32 m0, s10, 0x2000
	s_nop 0
	global_load_lds_dwordx4 v242, s[18:19]
	s_add_u32 m0, s10, 0x2400
	s_nop 0
	global_load_lds_dwordx4 v243, s[18:19]
	s_add_u32 m0, s10, 0x2800
	s_nop 0
	global_load_lds_dwordx4 v244, s[18:19]
	s_add_u32 m0, s10, 0x2c00
	s_nop 0
	global_load_lds_dwordx4 v245, s[18:19]
	s_add_u32 s16, s16, 64
	s_addc_u32 s17, s17, 0
	s_add_u32 s18, s18, 64
	s_addc_u32 s19, s19, 0
	s_add_u32 m0, s8, 0x6000
	s_nop 0
	global_load_lds_dwordx4 v240, s[16:17]
	s_add_u32 m0, s8, 0x6400
	s_nop 0
	global_load_lds_dwordx4 v241, s[16:17]
	s_add_u32 m0, s10, 0x8000
	s_nop 0
	global_load_lds_dwordx4 v242, s[18:19]
	s_add_u32 m0, s10, 0x8400
	s_nop 0
	global_load_lds_dwordx4 v243, s[18:19]
	s_add_u32 m0, s10, 0x8800
	s_nop 0
	global_load_lds_dwordx4 v244, s[18:19]
	s_add_u32 m0, s10, 0x8c00
	s_nop 0
	global_load_lds_dwordx4 v245, s[18:19]
	s_add_u32 s16, s16, 64
	s_addc_u32 s17, s17, 0
	s_add_u32 s18, s18, 64
	s_addc_u32 s19, s19, 0
	s_add_u32 m0, s8, 0xc000
	s_nop 0
	global_load_lds_dwordx4 v240, s[16:17]
	s_add_u32 m0, s8, 0xc400
	s_nop 0
	global_load_lds_dwordx4 v241, s[16:17]
	s_add_u32 m0, s10, 0xe000
	s_nop 0
	global_load_lds_dwordx4 v242, s[18:19]
	s_add_u32 m0, s10, 0xe400
	s_nop 0
	global_load_lds_dwordx4 v243, s[18:19]
	s_add_u32 m0, s10, 0xe800
	s_nop 0
	global_load_lds_dwordx4 v244, s[18:19]
	s_add_u32 m0, s10, 0xec00
	s_nop 0
	global_load_lds_dwordx4 v245, s[18:19]
	s_add_u32 s16, s16, 64
	s_addc_u32 s17, s17, 0
	s_add_u32 s18, s18, 64
	s_addc_u32 s19, s19, 0
	v_mov_b32_e32 v0, 0
	v_mov_b32_e32 v1, 0
	v_mov_b32_e32 v2, 0
	v_mov_b32_e32 v3, 0
	v_mov_b32_e32 v4, 0
	v_mov_b32_e32 v5, 0
	v_mov_b32_e32 v6, 0
	v_mov_b32_e32 v7, 0
	v_mov_b32_e32 v8, 0
	v_mov_b32_e32 v9, 0
	v_mov_b32_e32 v10, 0
	v_mov_b32_e32 v11, 0
	v_mov_b32_e32 v12, 0
	v_mov_b32_e32 v13, 0
	v_mov_b32_e32 v14, 0
	v_mov_b32_e32 v15, 0
	v_mov_b32_e32 v16, 0
	v_mov_b32_e32 v17, 0
	v_mov_b32_e32 v18, 0
	v_mov_b32_e32 v19, 0
	v_mov_b32_e32 v20, 0
	v_mov_b32_e32 v21, 0
	v_mov_b32_e32 v22, 0
	v_mov_b32_e32 v23, 0
	v_mov_b32_e32 v24, 0
	v_mov_b32_e32 v25, 0
	v_mov_b32_e32 v26, 0
	v_mov_b32_e32 v27, 0
	v_mov_b32_e32 v28, 0
	v_mov_b32_e32 v29, 0
	v_mov_b32_e32 v30, 0
	v_mov_b32_e32 v31, 0
	v_mov_b32_e32 v32, 0
	v_mov_b32_e32 v33, 0
	v_mov_b32_e32 v34, 0
	v_mov_b32_e32 v35, 0
	v_mov_b32_e32 v36, 0
	v_mov_b32_e32 v37, 0
	v_mov_b32_e32 v38, 0
	v_mov_b32_e32 v39, 0
	v_mov_b32_e32 v40, 0
	v_mov_b32_e32 v41, 0
	v_mov_b32_e32 v42, 0
	v_mov_b32_e32 v43, 0
	v_mov_b32_e32 v44, 0
	v_mov_b32_e32 v45, 0
	v_mov_b32_e32 v46, 0
	v_mov_b32_e32 v47, 0
	v_mov_b32_e32 v48, 0
	v_mov_b32_e32 v49, 0
	v_mov_b32_e32 v50, 0
	v_mov_b32_e32 v51, 0
	v_mov_b32_e32 v52, 0
	v_mov_b32_e32 v53, 0
	v_mov_b32_e32 v54, 0
	v_mov_b32_e32 v55, 0
	v_mov_b32_e32 v56, 0
	v_mov_b32_e32 v57, 0
	v_mov_b32_e32 v58, 0
	v_mov_b32_e32 v59, 0
	v_mov_b32_e32 v60, 0
	v_mov_b32_e32 v61, 0
	v_mov_b32_e32 v62, 0
; template <int NI> ...
;     ...
;   for (int kt = 0; kt < nk; kt += 2) {
;     G_LOAD(a0, b0, min((kt + 2) * 32, klast));
;     G_COMPUTE(0);
;     G_WRITE(a1, b1, 1);
;     __syncthreads();
;     G_LOAD(a1, b1, min((kt + 3) * 32, klast));
;     G_COMPUTE(1);
	v_mov_b32_e32 v63, 0
	v_mov_b32_e32 v64, 0
	v_mov_b32_e32 v65, 0
	v_mov_b32_e32 v66, 0
	v_mov_b32_e32 v67, 0
	v_mov_b32_e32 v68, 0
	v_mov_b32_e32 v69, 0
	v_mov_b32_e32 v70, 0
	v_mov_b32_e32 v71, 0
	v_mov_b32_e32 v72, 0
	v_mov_b32_e32 v73, 0
	v_mov_b32_e32 v74, 0
	v_mov_b32_e32 v75, 0
	v_mov_b32_e32 v76, 0
	v_mov_b32_e32 v77, 0
	v_mov_b32_e32 v78, 0
	v_mov_b32_e32 v79, 0
	v_mov_b32_e32 v80, 0
	v_mov_b32_e32 v81, 0
	v_mov_b32_e32 v82, 0
	v_mov_b32_e32 v83, 0
	v_mov_b32_e32 v84, 0
	v_mov_b32_e32 v85, 0
	v_mov_b32_e32 v86, 0
	v_mov_b32_e32 v87, 0
	v_mov_b32_e32 v88, 0
	v_mov_b32_e32 v89, 0
	v_mov_b32_e32 v90, 0
	v_mov_b32_e32 v91, 0
	v_mov_b32_e32 v92, 0
	v_mov_b32_e32 v93, 0
	v_mov_b32_e32 v94, 0
	v_mov_b32_e32 v95, 0
	v_mov_b32_e32 v96, 0
	v_mov_b32_e32 v97, 0
	v_mov_b32_e32 v98, 0
	v_mov_b32_e32 v99, 0
	v_mov_b32_e32 v100, 0
	v_mov_b32_e32 v101, 0
	v_mov_b32_e32 v102, 0
	v_mov_b32_e32 v103, 0
	v_mov_b32_e32 v104, 0
	v_mov_b32_e32 v105, 0
	v_mov_b32_e32 v106, 0
	v_mov_b32_e32 v107, 0
	v_mov_b32_e32 v108, 0
	v_mov_b32_e32 v109, 0
	v_mov_b32_e32 v110, 0
	v_mov_b32_e32 v111, 0
	v_mov_b32_e32 v112, 0
	v_mov_b32_e32 v113, 0
	v_mov_b32_e32 v114, 0
	v_mov_b32_e32 v115, 0
	v_mov_b32_e32 v116, 0
	v_mov_b32_e32 v117, 0
	v_mov_b32_e32 v118, 0
	v_mov_b32_e32 v119, 0
	v_mov_b32_e32 v120, 0
	v_mov_b32_e32 v121, 0
	v_mov_b32_e32 v122, 0
	v_mov_b32_e32 v123, 0
	v_mov_b32_e32 v124, 0
	v_mov_b32_e32 v125, 0
	v_mov_b32_e32 v126, 0
	v_mov_b32_e32 v127, 0
	s_waitcnt vmcnt(12)
	s_barrier
	ds_read_b128 v[128:131], v246 offset:0
	ds_read_b128 v[148:151], v247 offset:0
	ds_read_b128 v[152:155], v247 offset:1024
	ds_read_b128 v[132:135], v246 offset:1024
	ds_read_b128 v[156:159], v247 offset:2048
	ds_read_b128 v[160:163], v247 offset:3072
	ds_read_b128 v[136:139], v246 offset:2048
	ds_read_b128 v[168:171], v247 offset:4096
	ds_read_b128 v[172:175], v247 offset:5120
	ds_read_b128 v[140:143], v246 offset:3072
	ds_read_b128 v[176:179], v247 offset:6144
	ds_read_b128 v[180:183], v247 offset:7168
	s_mov_b32 s29, 0
.Lmlp2_kloop:
	s_waitcnt vmcnt(6) lgkmcnt(0)
	s_barrier
	v_mfma_f32_16x16x32_bf16 v[0:3], v[148:151], v[128:131], v[0:3]
	ds_read_b128 v[184:187], v246 offset:24576
	s_add_u32 m0, s8, 0x0
	v_mfma_f32_16x16x32_bf16 v[4:7], v[152:155], v[128:131], v[4:7]
	ds_read_b128 v[200:203], v247 offset:24576
	global_load_lds_dwordx4 v240, s[16:17]
	v_mfma_f32_16x16x32_bf16 v[8:11], v[156:159], v[128:131], v[8:11]
	ds_read_b128 v[204:207], v247 offset:25600
	s_add_u32 m0, s8, 0x400
	v_mfma_f32_16x16x32_bf16 v[12:15], v[160:163], v[128:131], v[12:15]
	ds_read_b128 v[188:191], v246 offset:25600
	global_load_lds_dwordx4 v241, s[16:17]
	v_mfma_f32_16x16x32_bf16 v[16:19], v[168:171], v[128:131], v[16:19]
	ds_read_b128 v[208:211], v247 offset:26624
	s_add_u32 m0, s10, 0x2000
	v_mfma_f32_16x16x32_bf16 v[20:23], v[172:175], v[128:131], v[20:23]
	ds_read_b128 v[212:215], v247 offset:27648
	global_load_lds_dwordx4 v242, s[18:19]
	v_mfma_f32_16x16x32_bf16 v[24:27], v[176:179], v[128:131], v[24:27]
	ds_read_b128 v[192:195], v246 offset:26624
	s_add_u32 m0, s10, 0x2400
	v_mfma_f32_16x16x32_bf16 v[28:31], v[180:183], v[128:131], v[28:31]
	ds_read_b128 v[216:219], v247 offset:28672
	global_load_lds_dwordx4 v243, s[18:19]
	v_mfma_f32_16x16x32_bf16 v[32:35], v[148:151], v[132:135], v[32:35]
	ds_read_b128 v[220:223], v247 offset:29696
	s_add_u32 m0, s10, 0x2800
	v_mfma_f32_16x16x32_bf16 v[36:39], v[152:155], v[132:135], v[36:39]
	ds_read_b128 v[196:199], v246 offset:27648
	global_load_lds_dwordx4 v244, s[18:19]
	v_mfma_f32_16x16x32_bf16 v[40:43], v[156:159], v[132:135], v[40:43]
	ds_read_b128 v[228:231], v247 offset:30720
	s_add_u32 m0, s10, 0x2c00
	v_mfma_f32_16x16x32_bf16 v[44:47], v[160:163], v[132:135], v[44:47]
	ds_read_b128 v[232:235], v247 offset:31744
	global_load_lds_dwordx4 v245, s[18:19]
	v_mfma_f32_16x16x32_bf16 v[48:51], v[168:171], v[132:135], v[48:51]
	s_add_u32 s16, s16, 64
	v_mfma_f32_16x16x32_bf16 v[52:55], v[172:175], v[132:135], v[52:55]
	s_addc_u32 s17, s17, 0
	v_mfma_f32_16x16x32_bf16 v[56:59], v[176:179], v[132:135], v[56:59]
	s_add_u32 s18, s18, 64
	v_mfma_f32_16x16x32_bf16 v[60:63], v[180:183], v[132:135], v[60:63]
	s_addc_u32 s19, s19, 0
	v_mfma_f32_16x16x32_bf16 v[64:67], v[148:151], v[136:139], v[64:67]
	v_mfma_f32_16x16x32_bf16 v[68:71], v[152:155], v[136:139], v[68:71]
	v_mfma_f32_16x16x32_bf16 v[72:75], v[156:159], v[136:139], v[72:75]
	v_mfma_f32_16x16x32_bf16 v[76:79], v[160:163], v[136:139], v[76:79]
	v_mfma_f32_16x16x32_bf16 v[80:83], v[168:171], v[136:139], v[80:83]
	v_mfma_f32_16x16x32_bf16 v[84:87], v[172:175], v[136:139], v[84:87]
	v_mfma_f32_16x16x32_bf16 v[88:91], v[176:179], v[136:139], v[88:91]
	v_mfma_f32_16x16x32_bf16 v[92:95], v[180:183], v[136:139], v[92:95]
	v_mfma_f32_16x16x32_bf16 v[96:99], v[148:151], v[140:143], v[96:99]
	v_mfma_f32_16x16x32_bf16 v[100:103], v[152:155], v[140:143], v[100:103]
	v_mfma_f32_16x16x32_bf16 v[104:107], v[156:159], v[140:143], v[104:107]
	v_mfma_f32_16x16x32_bf16 v[108:111], v[160:163], v[140:143], v[108:111]
	v_mfma_f32_16x16x32_bf16 v[112:115], v[168:171], v[140:143], v[112:115]
	v_mfma_f32_16x16x32_bf16 v[116:119], v[172:175], v[140:143], v[116:119]
	v_mfma_f32_16x16x32_bf16 v[120:123], v[176:179], v[140:143], v[120:123]
	v_mfma_f32_16x16x32_bf16 v[124:127], v[180:183], v[140:143], v[124:127]
	s_waitcnt vmcnt(6) lgkmcnt(0)
	s_barrier
; template <int NI> ...
;     ...
;   for (int kt = 0; kt < nk; kt += 2) {
;     G_LOAD(a0, b0, min((kt + 2) * 32, klast));
;     G_COMPUTE(0);
;     G_WRITE(a1, b1, 1);
;     __syncthreads();
;     G_LOAD(a1, b1, min((kt + 3) * 32, klast));
;     G_COMPUTE(1);
;     G_WRITE(a0, b0, 0);
;     __syncthreads();
;   }
	v_mfma_f32_16x16x32_bf16 v[0:3], v[200:203], v[184:187], v[0:3]
	ds_read_b128 v[128:131], v246 offset:49152
	s_add_u32 m0, s8, 0x6000
	v_mfma_f32_16x16x32_bf16 v[4:7], v[204:207], v[184:187], v[4:7]
	ds_read_b128 v[148:151], v247 offset:49152
	global_load_lds_dwordx4 v240, s[16:17]
	v_mfma_f32_16x16x32_bf16 v[8:11], v[208:211], v[184:187], v[8:11]
	ds_read_b128 v[152:155], v247 offset:50176
	s_add_u32 m0, s8, 0x6400
	v_mfma_f32_16x16x32_bf16 v[12:15], v[212:215], v[184:187], v[12:15]
	ds_read_b128 v[132:135], v246 offset:50176
	global_load_lds_dwordx4 v241, s[16:17]
	v_mfma_f32_16x16x32_bf16 v[16:19], v[216:219], v[184:187], v[16:19]
	ds_read_b128 v[156:159], v247 offset:51200
	s_add_u32 m0, s10, 0x8000
	v_mfma_f32_16x16x32_bf16 v[20:23], v[220:223], v[184:187], v[20:23]
	ds_read_b128 v[160:163], v247 offset:52224
	global_load_lds_dwordx4 v242, s[18:19]
	v_mfma_f32_16x16x32_bf16 v[24:27], v[228:231], v[184:187], v[24:27]
	ds_read_b128 v[136:139], v246 offset:51200
	s_add_u32 m0, s10, 0x8400
	v_mfma_f32_16x16x32_bf16 v[28:31], v[232:235], v[184:187], v[28:31]
	ds_read_b128 v[168:171], v247 offset:53248
	global_load_lds_dwordx4 v243, s[18:19]
	v_mfma_f32_16x16x32_bf16 v[32:35], v[200:203], v[188:191], v[32:35]
	ds_read_b128 v[172:175], v247 offset:54272
	s_add_u32 m0, s10, 0x8800
	v_mfma_f32_16x16x32_bf16 v[36:39], v[204:207], v[188:191], v[36:39]
	ds_read_b128 v[140:143], v246 offset:52224
	global_load_lds_dwordx4 v244, s[18:19]
	v_mfma_f32_16x16x32_bf16 v[40:43], v[208:211], v[188:191], v[40:43]
	ds_read_b128 v[176:179], v247 offset:55296
	s_add_u32 m0, s10, 0x8c00
	v_mfma_f32_16x16x32_bf16 v[44:47], v[212:215], v[188:191], v[44:47]
	ds_read_b128 v[180:183], v247 offset:56320
	global_load_lds_dwordx4 v245, s[18:19]
	v_mfma_f32_16x16x32_bf16 v[48:51], v[216:219], v[188:191], v[48:51]
	s_add_u32 s16, s16, 64
	v_mfma_f32_16x16x32_bf16 v[52:55], v[220:223], v[188:191], v[52:55]
	s_addc_u32 s17, s17, 0
	v_mfma_f32_16x16x32_bf16 v[56:59], v[228:231], v[188:191], v[56:59]
	s_add_u32 s18, s18, 64
	v_mfma_f32_16x16x32_bf16 v[60:63], v[232:235], v[188:191], v[60:63]
	s_addc_u32 s19, s19, 0
	v_mfma_f32_16x16x32_bf16 v[64:67], v[200:203], v[192:195], v[64:67]
	v_mfma_f32_16x16x32_bf16 v[68:71], v[204:207], v[192:195], v[68:71]
	v_mfma_f32_16x16x32_bf16 v[72:75], v[208:211], v[192:195], v[72:75]
	v_mfma_f32_16x16x32_bf16 v[76:79], v[212:215], v[192:195], v[76:79]
	v_mfma_f32_16x16x32_bf16 v[80:83], v[216:219], v[192:195], v[80:83]
	v_mfma_f32_16x16x32_bf16 v[84:87], v[220:223], v[192:195], v[84:87]
	v_mfma_f32_16x16x32_bf16 v[88:91], v[228:231], v[192:195], v[88:91]
	v_mfma_f32_16x16x32_bf16 v[92:95], v[232:235], v[192:195], v[92:95]
	v_mfma_f32_16x16x32_bf16 v[96:99], v[200:203], v[196:199], v[96:99]
	v_mfma_f32_16x16x32_bf16 v[100:103], v[204:207], v[196:199], v[100:103]
	v_mfma_f32_16x16x32_bf16 v[104:107], v[208:211], v[196:199], v[104:107]
	v_mfma_f32_16x16x32_bf16 v[108:111], v[212:215], v[196:199], v[108:111]
	v_mfma_f32_16x16x32_bf16 v[112:115], v[216:219], v[196:199], v[112:115]
	v_mfma_f32_16x16x32_bf16 v[116:119], v[220:223], v[196:199], v[116:119]
	v_mfma_f32_16x16x32_bf16 v[120:123], v[228:231], v[196:199], v[120:123]
	v_mfma_f32_16x16x32_bf16 v[124:127], v[232:235], v[196:199], v[124:127]
	s_waitcnt vmcnt(6) lgkmcnt(0)
	s_barrier
	v_mfma_f32_16x16x32_bf16 v[0:3], v[148:151], v[128:131], v[0:3]
	ds_read_b128 v[184:187], v246 offset:0
	s_add_u32 m0, s8, 0xc000
	v_mfma_f32_16x16x32_bf16 v[4:7], v[152:155], v[128:131], v[4:7]
	ds_read_b128 v[200:203], v247 offset:0
	global_load_lds_dwordx4 v240, s[16:17]
	v_mfma_f32_16x16x32_bf16 v[8:11], v[156:159], v[128:131], v[8:11]
	ds_read_b128 v[204:207], v247 offset:1024
	s_add_u32 m0, s8, 0xc400
	v_mfma_f32_16x16x32_bf16 v[12:15], v[160:163], v[128:131], v[12:15]
	ds_read_b128 v[188:191], v246 offset:1024
	global_load_lds_dwordx4 v241, s[16:17]
	v_mfma_f32_16x16x32_bf16 v[16:19], v[168:171], v[128:131], v[16:19]
	ds_read_b128 v[208:211], v247 offset:2048
	s_add_u32 m0, s10, 0xe000
	v_mfma_f32_16x16x32_bf16 v[20:23], v[172:175], v[128:131], v[20:23]
	ds_read_b128 v[212:215], v247 offset:3072
	global_load_lds_dwordx4 v242, s[18:19]
	v_mfma_f32_16x16x32_bf16 v[24:27], v[176:179], v[128:131], v[24:27]
	ds_read_b128 v[192:195], v246 offset:2048
	s_add_u32 m0, s10, 0xe400
	v_mfma_f32_16x16x32_bf16 v[28:31], v[180:183], v[128:131], v[28:31]
	ds_read_b128 v[216:219], v247 offset:4096
	global_load_lds_dwordx4 v243, s[18:19]
	v_mfma_f32_16x16x32_bf16 v[32:35], v[148:151], v[132:135], v[32:35]
	ds_read_b128 v[220:223], v247 offset:5120
	s_add_u32 m0, s10, 0xe800
	v_mfma_f32_16x16x32_bf16 v[36:39], v[152:155], v[132:135], v[36:39]
	ds_read_b128 v[196:199], v246 offset:3072
	global_load_lds_dwordx4 v244, s[18:19]
	v_mfma_f32_16x16x32_bf16 v[40:43], v[156:159], v[132:135], v[40:43]
	ds_read_b128 v[228:231], v247 offset:6144
	s_add_u32 m0, s10, 0xec00
	v_mfma_f32_16x16x32_bf16 v[44:47], v[160:163], v[132:135], v[44:47]
	ds_read_b128 v[232:235], v247 offset:7168
	global_load_lds_dwordx4 v245, s[18:19]
	v_mfma_f32_16x16x32_bf16 v[48:51], v[168:171], v[132:135], v[48:51]
	s_add_u32 s16, s16, 64
	v_mfma_f32_16x16x32_bf16 v[52:55], v[172:175], v[132:135], v[52:55]
	s_addc_u32 s17, s17, 0
	v_mfma_f32_16x16x32_bf16 v[56:59], v[176:179], v[132:135], v[56:59]
	s_add_u32 s18, s18, 64
	v_mfma_f32_16x16x32_bf16 v[60:63], v[180:183], v[132:135], v[60:63]
	s_addc_u32 s19, s19, 0
	v_mfma_f32_16x16x32_bf16 v[64:67], v[148:151], v[136:139], v[64:67]
	v_mfma_f32_16x16x32_bf16 v[68:71], v[152:155], v[136:139], v[68:71]
	v_mfma_f32_16x16x32_bf16 v[72:75], v[156:159], v[136:139], v[72:75]
	v_mfma_f32_16x16x32_bf16 v[76:79], v[160:163], v[136:139], v[76:79]
	v_mfma_f32_16x16x32_bf16 v[80:83], v[168:171], v[136:139], v[80:83]
	v_mfma_f32_16x16x32_bf16 v[84:87], v[172:175], v[136:139], v[84:87]
	v_mfma_f32_16x16x32_bf16 v[88:91], v[176:179], v[136:139], v[88:91]
	v_mfma_f32_16x16x32_bf16 v[92:95], v[180:183], v[136:139], v[92:95]
	v_mfma_f32_16x16x32_bf16 v[96:99], v[148:151], v[140:143], v[96:99]
	v_mfma_f32_16x16x32_bf16 v[100:103], v[152:155], v[140:143], v[100:103]
	v_mfma_f32_16x16x32_bf16 v[104:107], v[156:159], v[140:143], v[104:107]
	v_mfma_f32_16x16x32_bf16 v[108:111], v[160:163], v[140:143], v[108:111]
	v_mfma_f32_16x16x32_bf16 v[112:115], v[168:171], v[140:143], v[112:115]
	v_mfma_f32_16x16x32_bf16 v[116:119], v[172:175], v[140:143], v[116:119]
	v_mfma_f32_16x16x32_bf16 v[120:123], v[176:179], v[140:143], v[120:123]
	v_mfma_f32_16x16x32_bf16 v[124:127], v[180:183], v[140:143], v[124:127]
	s_waitcnt vmcnt(6) lgkmcnt(0)
	s_barrier
; template <int NI> ...
;     ...
;   for (int kt = 0; kt < nk; kt += 2) {
;     G_LOAD(a0, b0, min((kt + 2) * 32, klast));
;     G_COMPUTE(0);
;     G_WRITE(a1, b1, 1);
;     __syncthreads();
;     G_LOAD(a1, b1, min((kt + 3) * 32, klast));
;     G_COMPUTE(1);
;     G_WRITE(a0, b0, 0);
;     __syncthreads();
;   }
	v_mfma_f32_16x16x32_bf16 v[0:3], v[200:203], v[184:187], v[0:3]
	ds_read_b128 v[128:131], v246 offset:24576
	s_add_u32 m0, s8, 0x0
	v_mfma_f32_16x16x32_bf16 v[4:7], v[204:207], v[184:187], v[4:7]
	ds_read_b128 v[148:151], v247 offset:24576
	global_load_lds_dwordx4 v240, s[16:17]
	v_mfma_f32_16x16x32_bf16 v[8:11], v[208:211], v[184:187], v[8:11]
	ds_read_b128 v[152:155], v247 offset:25600
	s_add_u32 m0, s8, 0x400
	v_mfma_f32_16x16x32_bf16 v[12:15], v[212:215], v[184:187], v[12:15]
	ds_read_b128 v[132:135], v246 offset:25600
	global_load_lds_dwordx4 v241, s[16:17]
	v_mfma_f32_16x16x32_bf16 v[16:19], v[216:219], v[184:187], v[16:19]
	ds_read_b128 v[156:159], v247 offset:26624
	s_add_u32 m0, s10, 0x2000
	v_mfma_f32_16x16x32_bf16 v[20:23], v[220:223], v[184:187], v[20:23]
	ds_read_b128 v[160:163], v247 offset:27648
	global_load_lds_dwordx4 v242, s[18:19]
	v_mfma_f32_16x16x32_bf16 v[24:27], v[228:231], v[184:187], v[24:27]
	ds_read_b128 v[136:139], v246 offset:26624
	s_add_u32 m0, s10, 0x2400
	v_mfma_f32_16x16x32_bf16 v[28:31], v[232:235], v[184:187], v[28:31]
	ds_read_b128 v[168:171], v247 offset:28672
	global_load_lds_dwordx4 v243, s[18:19]
	v_mfma_f32_16x16x32_bf16 v[32:35], v[200:203], v[188:191], v[32:35]
	ds_read_b128 v[172:175], v247 offset:29696
	s_add_u32 m0, s10, 0x2800
	v_mfma_f32_16x16x32_bf16 v[36:39], v[204:207], v[188:191], v[36:39]
	ds_read_b128 v[140:143], v246 offset:27648
	global_load_lds_dwordx4 v244, s[18:19]
	v_mfma_f32_16x16x32_bf16 v[40:43], v[208:211], v[188:191], v[40:43]
	ds_read_b128 v[176:179], v247 offset:30720
	s_add_u32 m0, s10, 0x2c00
	v_mfma_f32_16x16x32_bf16 v[44:47], v[212:215], v[188:191], v[44:47]
	ds_read_b128 v[180:183], v247 offset:31744
	global_load_lds_dwordx4 v245, s[18:19]
	v_mfma_f32_16x16x32_bf16 v[48:51], v[216:219], v[188:191], v[48:51]
	s_add_u32 s16, s16, 64
	v_mfma_f32_16x16x32_bf16 v[52:55], v[220:223], v[188:191], v[52:55]
	s_addc_u32 s17, s17, 0
	v_mfma_f32_16x16x32_bf16 v[56:59], v[228:231], v[188:191], v[56:59]
	s_add_u32 s18, s18, 64
	v_mfma_f32_16x16x32_bf16 v[60:63], v[232:235], v[188:191], v[60:63]
	s_addc_u32 s19, s19, 0
	v_mfma_f32_16x16x32_bf16 v[64:67], v[200:203], v[192:195], v[64:67]
	v_mfma_f32_16x16x32_bf16 v[68:71], v[204:207], v[192:195], v[68:71]
	v_mfma_f32_16x16x32_bf16 v[72:75], v[208:211], v[192:195], v[72:75]
	v_mfma_f32_16x16x32_bf16 v[76:79], v[212:215], v[192:195], v[76:79]
	v_mfma_f32_16x16x32_bf16 v[80:83], v[216:219], v[192:195], v[80:83]
	v_mfma_f32_16x16x32_bf16 v[84:87], v[220:223], v[192:195], v[84:87]
	v_mfma_f32_16x16x32_bf16 v[88:91], v[228:231], v[192:195], v[88:91]
	v_mfma_f32_16x16x32_bf16 v[92:95], v[232:235], v[192:195], v[92:95]
	v_mfma_f32_16x16x32_bf16 v[96:99], v[200:203], v[196:199], v[96:99]
	v_mfma_f32_16x16x32_bf16 v[100:103], v[204:207], v[196:199], v[100:103]
	v_mfma_f32_16x16x32_bf16 v[104:107], v[208:211], v[196:199], v[104:107]
	v_mfma_f32_16x16x32_bf16 v[108:111], v[212:215], v[196:199], v[108:111]
	v_mfma_f32_16x16x32_bf16 v[112:115], v[216:219], v[196:199], v[112:115]
	v_mfma_f32_16x16x32_bf16 v[116:119], v[220:223], v[196:199], v[116:119]
	v_mfma_f32_16x16x32_bf16 v[120:123], v[228:231], v[196:199], v[120:123]
	v_mfma_f32_16x16x32_bf16 v[124:127], v[232:235], v[196:199], v[124:127]
	s_waitcnt vmcnt(6) lgkmcnt(0)
	s_barrier
	v_mfma_f32_16x16x32_bf16 v[0:3], v[148:151], v[128:131], v[0:3]
	ds_read_b128 v[184:187], v246 offset:49152
	s_add_u32 m0, s8, 0x6000
	v_mfma_f32_16x16x32_bf16 v[4:7], v[152:155], v[128:131], v[4:7]
	ds_read_b128 v[200:203], v247 offset:49152
	global_load_lds_dwordx4 v240, s[16:17]
	v_mfma_f32_16x16x32_bf16 v[8:11], v[156:159], v[128:131], v[8:11]
	ds_read_b128 v[204:207], v247 offset:50176
	s_add_u32 m0, s8, 0x6400
	v_mfma_f32_16x16x32_bf16 v[12:15], v[160:163], v[128:131], v[12:15]
	ds_read_b128 v[188:191], v246 offset:50176
	global_load_lds_dwordx4 v241, s[16:17]
	v_mfma_f32_16x16x32_bf16 v[16:19], v[168:171], v[128:131], v[16:19]
	ds_read_b128 v[208:211], v247 offset:51200
	s_add_u32 m0, s10, 0x8000
	v_mfma_f32_16x16x32_bf16 v[20:23], v[172:175], v[128:131], v[20:23]
	ds_read_b128 v[212:215], v247 offset:52224
	global_load_lds_dwordx4 v242, s[18:19]
	v_mfma_f32_16x16x32_bf16 v[24:27], v[176:179], v[128:131], v[24:27]
	ds_read_b128 v[192:195], v246 offset:51200
	s_add_u32 m0, s10, 0x8400
	v_mfma_f32_16x16x32_bf16 v[28:31], v[180:183], v[128:131], v[28:31]
	ds_read_b128 v[216:219], v247 offset:53248
	global_load_lds_dwordx4 v243, s[18:19]
	v_mfma_f32_16x16x32_bf16 v[32:35], v[148:151], v[132:135], v[32:35]
	ds_read_b128 v[220:223], v247 offset:54272
	s_add_u32 m0, s10, 0x8800
	v_mfma_f32_16x16x32_bf16 v[36:39], v[152:155], v[132:135], v[36:39]
	ds_read_b128 v[196:199], v246 offset:52224
	global_load_lds_dwordx4 v244, s[18:19]
	v_mfma_f32_16x16x32_bf16 v[40:43], v[156:159], v[132:135], v[40:43]
	ds_read_b128 v[228:231], v247 offset:55296
	s_add_u32 m0, s10, 0x8c00
	v_mfma_f32_16x16x32_bf16 v[44:47], v[160:163], v[132:135], v[44:47]
	ds_read_b128 v[232:235], v247 offset:56320
	global_load_lds_dwordx4 v245, s[18:19]
	v_mfma_f32_16x16x32_bf16 v[48:51], v[168:171], v[132:135], v[48:51]
	s_add_u32 s16, s16, 64
	v_mfma_f32_16x16x32_bf16 v[52:55], v[172:175], v[132:135], v[52:55]
	s_addc_u32 s17, s17, 0
	v_mfma_f32_16x16x32_bf16 v[56:59], v[176:179], v[132:135], v[56:59]
	s_add_u32 s18, s18, 64
	v_mfma_f32_16x16x32_bf16 v[60:63], v[180:183], v[132:135], v[60:63]
	s_addc_u32 s19, s19, 0
	v_mfma_f32_16x16x32_bf16 v[64:67], v[148:151], v[136:139], v[64:67]
	v_mfma_f32_16x16x32_bf16 v[68:71], v[152:155], v[136:139], v[68:71]
	v_mfma_f32_16x16x32_bf16 v[72:75], v[156:159], v[136:139], v[72:75]
	v_mfma_f32_16x16x32_bf16 v[76:79], v[160:163], v[136:139], v[76:79]
	v_mfma_f32_16x16x32_bf16 v[80:83], v[168:171], v[136:139], v[80:83]
	v_mfma_f32_16x16x32_bf16 v[84:87], v[172:175], v[136:139], v[84:87]
	v_mfma_f32_16x16x32_bf16 v[88:91], v[176:179], v[136:139], v[88:91]
	v_mfma_f32_16x16x32_bf16 v[92:95], v[180:183], v[136:139], v[92:95]
	v_mfma_f32_16x16x32_bf16 v[96:99], v[148:151], v[140:143], v[96:99]
	v_mfma_f32_16x16x32_bf16 v[100:103], v[152:155], v[140:143], v[100:103]
	v_mfma_f32_16x16x32_bf16 v[104:107], v[156:159], v[140:143], v[104:107]
	v_mfma_f32_16x16x32_bf16 v[108:111], v[160:163], v[140:143], v[108:111]
	v_mfma_f32_16x16x32_bf16 v[112:115], v[168:171], v[140:143], v[112:115]
	v_mfma_f32_16x16x32_bf16 v[116:119], v[172:175], v[140:143], v[116:119]
	v_mfma_f32_16x16x32_bf16 v[120:123], v[176:179], v[140:143], v[120:123]
	v_mfma_f32_16x16x32_bf16 v[124:127], v[180:183], v[140:143], v[124:127]
	s_waitcnt vmcnt(6) lgkmcnt(0)
	s_barrier
; template <int NI> ...
;     ...
;   for (int kt = 0; kt < nk; kt += 2) {
;     G_LOAD(a0, b0, min((kt + 2) * 32, klast));
;     G_COMPUTE(0);
;     G_WRITE(a1, b1, 1);
;     __syncthreads();
;     G_LOAD(a1, b1, min((kt + 3) * 32, klast));
;     G_COMPUTE(1);
;     G_WRITE(a0, b0, 0);
;     __syncthreads();
;   }
;   asm volatile("s_nop 15\n\ts_nop 15" ::: "memory");
; __device__ void phase_proj_res(CParams& p, int l, int tm, int tn, char* smem, const bf16_t* A, int K,
;                                const bf16_t* Bt, int gate_off, float gscale) {
;     ...
;   const float* md = p.mod + ((size_t)l * 3 + modvec_of_tok(row0)) * 6144 + gate_off;
;   EPI_LOOP({
;     float* xp = xrow(p, row0 + rl) + col0 + cl;
	v_mfma_f32_16x16x32_bf16 v[0:3], v[200:203], v[184:187], v[0:3]
	ds_read_b128 v[128:131], v246 offset:0
	s_add_u32 m0, s8, 0xc000
	v_mfma_f32_16x16x32_bf16 v[4:7], v[204:207], v[184:187], v[4:7]
	ds_read_b128 v[148:151], v247 offset:0
	global_load_lds_dwordx4 v240, s[16:17]
	v_mfma_f32_16x16x32_bf16 v[8:11], v[208:211], v[184:187], v[8:11]
	ds_read_b128 v[152:155], v247 offset:1024
	s_add_u32 m0, s8, 0xc400
	v_mfma_f32_16x16x32_bf16 v[12:15], v[212:215], v[184:187], v[12:15]
	ds_read_b128 v[132:135], v246 offset:1024
	global_load_lds_dwordx4 v241, s[16:17]
	v_mfma_f32_16x16x32_bf16 v[16:19], v[216:219], v[184:187], v[16:19]
	ds_read_b128 v[156:159], v247 offset:2048
	s_add_u32 m0, s10, 0xe000
	v_mfma_f32_16x16x32_bf16 v[20:23], v[220:223], v[184:187], v[20:23]
	ds_read_b128 v[160:163], v247 offset:3072
	global_load_lds_dwordx4 v242, s[18:19]
	v_mfma_f32_16x16x32_bf16 v[24:27], v[228:231], v[184:187], v[24:27]
	ds_read_b128 v[136:139], v246 offset:2048
	s_add_u32 m0, s10, 0xe400
	v_mfma_f32_16x16x32_bf16 v[28:31], v[232:235], v[184:187], v[28:31]
	ds_read_b128 v[168:171], v247 offset:4096
	global_load_lds_dwordx4 v243, s[18:19]
	v_mfma_f32_16x16x32_bf16 v[32:35], v[200:203], v[188:191], v[32:35]
	ds_read_b128 v[172:175], v247 offset:5120
	s_add_u32 m0, s10, 0xe800
	v_mfma_f32_16x16x32_bf16 v[36:39], v[204:207], v[188:191], v[36:39]
	ds_read_b128 v[140:143], v246 offset:3072
	global_load_lds_dwordx4 v244, s[18:19]
	v_mfma_f32_16x16x32_bf16 v[40:43], v[208:211], v[188:191], v[40:43]
	ds_read_b128 v[176:179], v247 offset:6144
	s_add_u32 m0, s10, 0xec00
	v_mfma_f32_16x16x32_bf16 v[44:47], v[212:215], v[188:191], v[44:47]
	ds_read_b128 v[180:183], v247 offset:7168
	global_load_lds_dwordx4 v245, s[18:19]
	v_mfma_f32_16x16x32_bf16 v[48:51], v[216:219], v[188:191], v[48:51]
	s_add_u32 s16, s16, 64
	v_mfma_f32_16x16x32_bf16 v[52:55], v[220:223], v[188:191], v[52:55]
	s_addc_u32 s17, s17, 0
	v_mfma_f32_16x16x32_bf16 v[56:59], v[228:231], v[188:191], v[56:59]
	s_add_u32 s18, s18, 64
	v_mfma_f32_16x16x32_bf16 v[60:63], v[232:235], v[188:191], v[60:63]
	s_addc_u32 s19, s19, 0
	v_mfma_f32_16x16x32_bf16 v[64:67], v[200:203], v[192:195], v[64:67]
	v_mfma_f32_16x16x32_bf16 v[68:71], v[204:207], v[192:195], v[68:71]
	v_mfma_f32_16x16x32_bf16 v[72:75], v[208:211], v[192:195], v[72:75]
	v_mfma_f32_16x16x32_bf16 v[76:79], v[212:215], v[192:195], v[76:79]
	v_mfma_f32_16x16x32_bf16 v[80:83], v[216:219], v[192:195], v[80:83]
	v_mfma_f32_16x16x32_bf16 v[84:87], v[220:223], v[192:195], v[84:87]
	v_mfma_f32_16x16x32_bf16 v[88:91], v[228:231], v[192:195], v[88:91]
	v_mfma_f32_16x16x32_bf16 v[92:95], v[232:235], v[192:195], v[92:95]
	v_mfma_f32_16x16x32_bf16 v[96:99], v[200:203], v[196:199], v[96:99]
	v_mfma_f32_16x16x32_bf16 v[100:103], v[204:207], v[196:199], v[100:103]
	v_mfma_f32_16x16x32_bf16 v[104:107], v[208:211], v[196:199], v[104:107]
	v_mfma_f32_16x16x32_bf16 v[108:111], v[212:215], v[196:199], v[108:111]
	v_mfma_f32_16x16x32_bf16 v[112:115], v[216:219], v[196:199], v[112:115]
	v_mfma_f32_16x16x32_bf16 v[116:119], v[220:223], v[196:199], v[116:119]
	v_mfma_f32_16x16x32_bf16 v[120:123], v[228:231], v[196:199], v[120:123]
	v_mfma_f32_16x16x32_bf16 v[124:127], v[232:235], v[196:199], v[124:127]
	s_add_u32 s29, s29, 1
	s_cmp_lt_u32 s29, 21
	s_cbranch_scc1 .Lmlp2_kloop
	s_waitcnt vmcnt(6) lgkmcnt(0)
	s_barrier
	v_mfma_f32_16x16x32_bf16 v[0:3], v[148:151], v[128:131], v[0:3]
	ds_read_b128 v[184:187], v246 offset:24576
	s_add_u32 m0, s8, 0x0
	v_mfma_f32_16x16x32_bf16 v[4:7], v[152:155], v[128:131], v[4:7]
	ds_read_b128 v[200:203], v247 offset:24576
	global_load_lds_dwordx4 v240, s[16:17]
	v_mfma_f32_16x16x32_bf16 v[8:11], v[156:159], v[128:131], v[8:11]
	ds_read_b128 v[204:207], v247 offset:25600
	s_add_u32 m0, s8, 0x400
	v_mfma_f32_16x16x32_bf16 v[12:15], v[160:163], v[128:131], v[12:15]
	ds_read_b128 v[188:191], v246 offset:25600
	global_load_lds_dwordx4 v241, s[16:17]
	v_mfma_f32_16x16x32_bf16 v[16:19], v[168:171], v[128:131], v[16:19]
	ds_read_b128 v[208:211], v247 offset:26624
	s_add_u32 m0, s10, 0x2000
	v_mfma_f32_16x16x32_bf16 v[20:23], v[172:175], v[128:131], v[20:23]
	ds_read_b128 v[212:215], v247 offset:27648
	global_load_lds_dwordx4 v242, s[18:19]
	v_mfma_f32_16x16x32_bf16 v[24:27], v[176:179], v[128:131], v[24:27]
	ds_read_b128 v[192:195], v246 offset:26624
	s_add_u32 m0, s10, 0x2400
	v_mfma_f32_16x16x32_bf16 v[28:31], v[180:183], v[128:131], v[28:31]
	ds_read_b128 v[216:219], v247 offset:28672
	global_load_lds_dwordx4 v243, s[18:19]
	v_mfma_f32_16x16x32_bf16 v[32:35], v[148:151], v[132:135], v[32:35]
	ds_read_b128 v[220:223], v247 offset:29696
	s_add_u32 m0, s10, 0x2800
	v_mfma_f32_16x16x32_bf16 v[36:39], v[152:155], v[132:135], v[36:39]
	ds_read_b128 v[196:199], v246 offset:27648
	global_load_lds_dwordx4 v244, s[18:19]
	v_mfma_f32_16x16x32_bf16 v[40:43], v[156:159], v[132:135], v[40:43]
	ds_read_b128 v[228:231], v247 offset:30720
	s_add_u32 m0, s10, 0x2c00
	v_mfma_f32_16x16x32_bf16 v[44:47], v[160:163], v[132:135], v[44:47]
	ds_read_b128 v[232:235], v247 offset:31744
	global_load_lds_dwordx4 v245, s[18:19]
	v_mfma_f32_16x16x32_bf16 v[48:51], v[168:171], v[132:135], v[48:51]
	s_add_u32 s16, s16, 64
	v_mfma_f32_16x16x32_bf16 v[52:55], v[172:175], v[132:135], v[52:55]
	s_addc_u32 s17, s17, 0
	v_mfma_f32_16x16x32_bf16 v[56:59], v[176:179], v[132:135], v[56:59]
	s_add_u32 s18, s18, 64
	v_mfma_f32_16x16x32_bf16 v[60:63], v[180:183], v[132:135], v[60:63]
	s_addc_u32 s19, s19, 0
	v_mfma_f32_16x16x32_bf16 v[64:67], v[148:151], v[136:139], v[64:67]
	v_mfma_f32_16x16x32_bf16 v[68:71], v[152:155], v[136:139], v[68:71]
	v_mfma_f32_16x16x32_bf16 v[72:75], v[156:159], v[136:139], v[72:75]
	v_mfma_f32_16x16x32_bf16 v[76:79], v[160:163], v[136:139], v[76:79]
	v_mfma_f32_16x16x32_bf16 v[80:83], v[168:171], v[136:139], v[80:83]
	v_mfma_f32_16x16x32_bf16 v[84:87], v[172:175], v[136:139], v[84:87]
	v_mfma_f32_16x16x32_bf16 v[88:91], v[176:179], v[136:139], v[88:91]
	v_mfma_f32_16x16x32_bf16 v[92:95], v[180:183], v[136:139], v[92:95]
	v_mfma_f32_16x16x32_bf16 v[96:99], v[148:151], v[140:143], v[96:99]
	v_mfma_f32_16x16x32_bf16 v[100:103], v[152:155], v[140:143], v[100:103]
	v_mfma_f32_16x16x32_bf16 v[104:107], v[156:159], v[140:143], v[104:107]
	v_mfma_f32_16x16x32_bf16 v[108:111], v[160:163], v[140:143], v[108:111]
	v_mfma_f32_16x16x32_bf16 v[112:115], v[168:171], v[140:143], v[112:115]
	v_mfma_f32_16x16x32_bf16 v[116:119], v[172:175], v[140:143], v[116:119]
	v_mfma_f32_16x16x32_bf16 v[120:123], v[176:179], v[140:143], v[120:123]
	v_mfma_f32_16x16x32_bf16 v[124:127], v[180:183], v[140:143], v[124:127]
	s_waitcnt vmcnt(6) lgkmcnt(0)
	s_barrier
; template <int NI> ...
;     ...
;   for (int kt = 0; kt < nk; kt += 2) {
;     G_LOAD(a0, b0, min((kt + 2) * 32, klast));
;     G_COMPUTE(0);
;     G_WRITE(a1, b1, 1);
;     __syncthreads();
;     G_LOAD(a1, b1, min((kt + 3) * 32, klast));
;     G_COMPUTE(1);
;     G_WRITE(a0, b0, 0);
;     __syncthreads();
;   }
;   asm volatile("s_nop 15\n\ts_nop 15" ::: "memory");
; __device__ void phase_proj_res(CParams& p, int l, int tm, int tn, char* smem, const bf16_t* A, int K,
;                                const bf16_t* Bt, int gate_off, float gscale) {
;     ...
;   const float* md = p.mod + ((size_t)l * 3 + modvec_of_tok(row0)) * 6144 + gate_off;
;   EPI_LOOP({
;     float* xp = xrow(p, row0 + rl) + col0 + cl;
;     *xp = *xp + gscale * md[col0 + cl] * acc[mi][ni][j];
;   })
	v_mfma_f32_16x16x32_bf16 v[0:3], v[200:203], v[184:187], v[0:3]
	ds_read_b128 v[128:131], v246 offset:49152
	s_add_u32 m0, s8, 0x6000
	v_mfma_f32_16x16x32_bf16 v[4:7], v[204:207], v[184:187], v[4:7]
	ds_read_b128 v[148:151], v247 offset:49152
	global_load_lds_dwordx4 v240, s[16:17]
	v_mfma_f32_16x16x32_bf16 v[8:11], v[208:211], v[184:187], v[8:11]
	ds_read_b128 v[152:155], v247 offset:50176
	s_add_u32 m0, s8, 0x6400
	v_mfma_f32_16x16x32_bf16 v[12:15], v[212:215], v[184:187], v[12:15]
	ds_read_b128 v[132:135], v246 offset:50176
	global_load_lds_dwordx4 v241, s[16:17]
	v_mfma_f32_16x16x32_bf16 v[16:19], v[216:219], v[184:187], v[16:19]
	ds_read_b128 v[156:159], v247 offset:51200
	s_add_u32 m0, s10, 0x8000
	v_mfma_f32_16x16x32_bf16 v[20:23], v[220:223], v[184:187], v[20:23]
	ds_read_b128 v[160:163], v247 offset:52224
	global_load_lds_dwordx4 v242, s[18:19]
	v_mfma_f32_16x16x32_bf16 v[24:27], v[228:231], v[184:187], v[24:27]
	ds_read_b128 v[136:139], v246 offset:51200
	s_add_u32 m0, s10, 0x8400
	v_mfma_f32_16x16x32_bf16 v[28:31], v[232:235], v[184:187], v[28:31]
	ds_read_b128 v[168:171], v247 offset:53248
	global_load_lds_dwordx4 v243, s[18:19]
	v_mfma_f32_16x16x32_bf16 v[32:35], v[200:203], v[188:191], v[32:35]
	ds_read_b128 v[172:175], v247 offset:54272
	s_add_u32 m0, s10, 0x8800
	v_mfma_f32_16x16x32_bf16 v[36:39], v[204:207], v[188:191], v[36:39]
	ds_read_b128 v[140:143], v246 offset:52224
	global_load_lds_dwordx4 v244, s[18:19]
	v_mfma_f32_16x16x32_bf16 v[40:43], v[208:211], v[188:191], v[40:43]
	ds_read_b128 v[176:179], v247 offset:55296
	s_add_u32 m0, s10, 0x8c00
	v_mfma_f32_16x16x32_bf16 v[44:47], v[212:215], v[188:191], v[44:47]
	ds_read_b128 v[180:183], v247 offset:56320
	global_load_lds_dwordx4 v245, s[18:19]
	v_mfma_f32_16x16x32_bf16 v[48:51], v[216:219], v[188:191], v[48:51]
	s_add_u32 s16, s16, 64
	v_mfma_f32_16x16x32_bf16 v[52:55], v[220:223], v[188:191], v[52:55]
	s_addc_u32 s17, s17, 0
	v_mfma_f32_16x16x32_bf16 v[56:59], v[228:231], v[188:191], v[56:59]
	s_add_u32 s18, s18, 64
	v_mfma_f32_16x16x32_bf16 v[60:63], v[232:235], v[188:191], v[60:63]
	s_addc_u32 s19, s19, 0
	v_mfma_f32_16x16x32_bf16 v[64:67], v[200:203], v[192:195], v[64:67]
	v_mfma_f32_16x16x32_bf16 v[68:71], v[204:207], v[192:195], v[68:71]
	v_mfma_f32_16x16x32_bf16 v[72:75], v[208:211], v[192:195], v[72:75]
	v_mfma_f32_16x16x32_bf16 v[76:79], v[212:215], v[192:195], v[76:79]
	v_mfma_f32_16x16x32_bf16 v[80:83], v[216:219], v[192:195], v[80:83]
	v_mfma_f32_16x16x32_bf16 v[84:87], v[220:223], v[192:195], v[84:87]
	v_mfma_f32_16x16x32_bf16 v[88:91], v[228:231], v[192:195], v[88:91]
	v_mfma_f32_16x16x32_bf16 v[92:95], v[232:235], v[192:195], v[92:95]
	v_mfma_f32_16x16x32_bf16 v[96:99], v[200:203], v[196:199], v[96:99]
	v_mfma_f32_16x16x32_bf16 v[100:103], v[204:207], v[196:199], v[100:103]
	v_mfma_f32_16x16x32_bf16 v[104:107], v[208:211], v[196:199], v[104:107]
	v_mfma_f32_16x16x32_bf16 v[108:111], v[212:215], v[196:199], v[108:111]
	v_mfma_f32_16x16x32_bf16 v[112:115], v[216:219], v[196:199], v[112:115]
	v_mfma_f32_16x16x32_bf16 v[116:119], v[220:223], v[196:199], v[116:119]
	v_mfma_f32_16x16x32_bf16 v[120:123], v[228:231], v[196:199], v[120:123]
	v_mfma_f32_16x16x32_bf16 v[124:127], v[232:235], v[196:199], v[124:127]
	s_waitcnt vmcnt(0) lgkmcnt(0)
	s_barrier
	ds_write_b128 v145, v[236:239] offset:40960
	s_nop 15
	s_nop 15
	s_mul_i32 s40, s0, 3
	s_lshr_b32 s41, s32, 13
	s_add_u32 s40, s40, s41
	s_mul_i32 s40, s40, 6144
	s_add_u32 s40, s40, s28
	s_add_u32 s40, s40, 5120
	s_lshl_b32 s40, s40, 2
	s_add_u32 s26, s26, s40
	s_addc_u32 s27, s27, 0
	s_lshl_b32 s40, s32, 12
	s_lshl_b32 s41, s28, 2
	s_add_u32 s40, s40, s41
	s_add_u32 s22, s22, s40
	s_addc_u32 s23, s23, 0
	global_load_dwordx4 v[148:151], v249, s[26:27] offset:0
	global_load_dwordx4 v[152:155], v249, s[26:27] offset:64
	global_load_dwordx4 v[156:159], v249, s[26:27] offset:128
	global_load_dwordx4 v[160:163], v249, s[26:27] offset:192
	global_load_dwordx4 v[168:171], v249, s[26:27] offset:256
	global_load_dwordx4 v[172:175], v249, s[26:27] offset:320
	global_load_dwordx4 v[176:179], v249, s[26:27] offset:384
	global_load_dwordx4 v[180:183], v249, s[26:27] offset:448
	global_load_dwordx4 v[200:203], v248, s[22:23] offset:0
	global_load_dwordx4 v[204:207], v248, s[22:23] offset:64
	global_load_dwordx4 v[208:211], v248, s[22:23] offset:128
	global_load_dwordx4 v[212:215], v248, s[22:23] offset:192
	global_load_dwordx4 v[216:219], v248, s[22:23] offset:256
	global_load_dwordx4 v[220:223], v248, s[22:23] offset:320
	global_load_dwordx4 v[228:231], v248, s[22:23] offset:384
	global_load_dwordx4 v[232:235], v248, s[22:23] offset:448
	s_add_u32 s22, s22, 0x10000
	s_addc_u32 s23, s23, 0
	global_load_dwordx4 v[128:131], v248, s[22:23] offset:0
	global_load_dwordx4 v[132:135], v248, s[22:23] offset:64
	global_load_dwordx4 v[136:139], v248, s[22:23] offset:128
	global_load_dwordx4 v[140:143], v248, s[22:23] offset:192
	global_load_dwordx4 v[184:187], v248, s[22:23] offset:256
	global_load_dwordx4 v[188:191], v248, s[22:23] offset:320
	global_load_dwordx4 v[192:195], v248, s[22:23] offset:384
	global_load_dwordx4 v[196:199], v248, s[22:23] offset:448
	s_sub_u32 s22, s22, 0x10000
	s_subb_u32 s23, s23, 0
	s_waitcnt vmcnt(8)
; __device__ void phase_proj_res(CParams& p, int l, int tm, int tn, char* smem, const bf16_t* A, int K,
;                                const bf16_t* Bt, int gate_off, float gscale) {
;     ...
;   const float* md = p.mod + ((size_t)l * 3 + modvec_of_tok(row0)) * 6144 + gate_off;
;   EPI_LOOP({
;     float* xp = xrow(p, row0 + rl) + col0 + cl;
;     *xp = *xp + gscale * md[col0 + cl] * acc[mi][ni][j];
;   })
	v_fmac_f32_e32 v200, v148, v0
	v_fmac_f32_e32 v201, v149, v1
	v_fmac_f32_e32 v202, v150, v2
	v_fmac_f32_e32 v203, v151, v3
	v_fmac_f32_e32 v204, v152, v4
	v_fmac_f32_e32 v205, v153, v5
	v_fmac_f32_e32 v206, v154, v6
	v_fmac_f32_e32 v207, v155, v7
	v_fmac_f32_e32 v208, v156, v8
	v_fmac_f32_e32 v209, v157, v9
	v_fmac_f32_e32 v210, v158, v10
	v_fmac_f32_e32 v211, v159, v11
	v_fmac_f32_e32 v212, v160, v12
	v_fmac_f32_e32 v213, v161, v13
	v_fmac_f32_e32 v214, v162, v14
	v_fmac_f32_e32 v215, v163, v15
	v_fmac_f32_e32 v216, v168, v16
	v_fmac_f32_e32 v217, v169, v17
	v_fmac_f32_e32 v218, v170, v18
	v_fmac_f32_e32 v219, v171, v19
	v_fmac_f32_e32 v220, v172, v20
	v_fmac_f32_e32 v221, v173, v21
	v_fmac_f32_e32 v222, v174, v22
	v_fmac_f32_e32 v223, v175, v23
	v_fmac_f32_e32 v228, v176, v24
	v_fmac_f32_e32 v229, v177, v25
	v_fmac_f32_e32 v230, v178, v26
	v_fmac_f32_e32 v231, v179, v27
	v_fmac_f32_e32 v232, v180, v28
	v_fmac_f32_e32 v233, v181, v29
	v_fmac_f32_e32 v234, v182, v30
	v_fmac_f32_e32 v235, v183, v31
	global_store_dwordx4 v248, v[200:203], s[22:23] offset:0
	global_store_dwordx4 v248, v[204:207], s[22:23] offset:64
	global_store_dwordx4 v248, v[208:211], s[22:23] offset:128
	global_store_dwordx4 v248, v[212:215], s[22:23] offset:192
	global_store_dwordx4 v248, v[216:219], s[22:23] offset:256
	global_store_dwordx4 v248, v[220:223], s[22:23] offset:320
	global_store_dwordx4 v248, v[228:231], s[22:23] offset:384
	global_store_dwordx4 v248, v[232:235], s[22:23] offset:448
	s_add_u32 s22, s22, 0x10000
	s_addc_u32 s23, s23, 0
	s_add_u32 s22, s22, 0x10000
	s_addc_u32 s23, s23, 0
	global_load_dwordx4 v[200:203], v248, s[22:23] offset:0
	global_load_dwordx4 v[204:207], v248, s[22:23] offset:64
	global_load_dwordx4 v[208:211], v248, s[22:23] offset:128
	global_load_dwordx4 v[212:215], v248, s[22:23] offset:192
	global_load_dwordx4 v[216:219], v248, s[22:23] offset:256
	global_load_dwordx4 v[220:223], v248, s[22:23] offset:320
	global_load_dwordx4 v[228:231], v248, s[22:23] offset:384
	global_load_dwordx4 v[232:235], v248, s[22:23] offset:448
	s_sub_u32 s22, s22, 0x10000
	s_subb_u32 s23, s23, 0
	s_waitcnt vmcnt(8)
	v_fmac_f32_e32 v128, v148, v32
	v_fmac_f32_e32 v129, v149, v33
	v_fmac_f32_e32 v130, v150, v34
	v_fmac_f32_e32 v131, v151, v35
	v_fmac_f32_e32 v132, v152, v36
	v_fmac_f32_e32 v133, v153, v37
	v_fmac_f32_e32 v134, v154, v38
	v_fmac_f32_e32 v135, v155, v39
	v_fmac_f32_e32 v136, v156, v40
	v_fmac_f32_e32 v137, v157, v41
	v_fmac_f32_e32 v138, v158, v42
	v_fmac_f32_e32 v139, v159, v43
	v_fmac_f32_e32 v140, v160, v44
	v_fmac_f32_e32 v141, v161, v45
	v_fmac_f32_e32 v142, v162, v46
	v_fmac_f32_e32 v143, v163, v47
	v_fmac_f32_e32 v184, v168, v48
	v_fmac_f32_e32 v185, v169, v49
	v_fmac_f32_e32 v186, v170, v50
	v_fmac_f32_e32 v187, v171, v51
	v_fmac_f32_e32 v188, v172, v52
	v_fmac_f32_e32 v189, v173, v53
	v_fmac_f32_e32 v190, v174, v54
	v_fmac_f32_e32 v191, v175, v55
	v_fmac_f32_e32 v192, v176, v56
	v_fmac_f32_e32 v193, v177, v57
	v_fmac_f32_e32 v194, v178, v58
	v_fmac_f32_e32 v195, v179, v59
	v_fmac_f32_e32 v196, v180, v60
	v_fmac_f32_e32 v197, v181, v61
	v_fmac_f32_e32 v198, v182, v62
	v_fmac_f32_e32 v199, v183, v63
	global_store_dwordx4 v248, v[128:131], s[22:23] offset:0
	global_store_dwordx4 v248, v[132:135], s[22:23] offset:64
	global_store_dwordx4 v248, v[136:139], s[22:23] offset:128
	global_store_dwordx4 v248, v[140:143], s[22:23] offset:192
	global_store_dwordx4 v248, v[184:187], s[22:23] offset:256
	global_store_dwordx4 v248, v[188:191], s[22:23] offset:320
	global_store_dwordx4 v248, v[192:195], s[22:23] offset:384
	global_store_dwordx4 v248, v[196:199], s[22:23] offset:448
	s_add_u32 s22, s22, 0x10000
	s_addc_u32 s23, s23, 0
	s_add_u32 s22, s22, 0x10000
	s_addc_u32 s23, s23, 0
	global_load_dwordx4 v[128:131], v248, s[22:23] offset:0
	global_load_dwordx4 v[132:135], v248, s[22:23] offset:64
	global_load_dwordx4 v[136:139], v248, s[22:23] offset:128
	global_load_dwordx4 v[140:143], v248, s[22:23] offset:192
	global_load_dwordx4 v[184:187], v248, s[22:23] offset:256
	global_load_dwordx4 v[188:191], v248, s[22:23] offset:320
	global_load_dwordx4 v[192:195], v248, s[22:23] offset:384
	global_load_dwordx4 v[196:199], v248, s[22:23] offset:448
	s_sub_u32 s22, s22, 0x10000
	s_subb_u32 s23, s23, 0
	s_waitcnt vmcnt(8)
; __device__ void phase_proj_res(CParams& p, int l, int tm, int tn, char* smem, const bf16_t* A, int K,
;                                const bf16_t* Bt, int gate_off, float gscale) {
;     ...
;   const float* md = p.mod + ((size_t)l * 3 + modvec_of_tok(row0)) * 6144 + gate_off;
;   EPI_LOOP({
;     float* xp = xrow(p, row0 + rl) + col0 + cl;
;     *xp = *xp + gscale * md[col0 + cl] * acc[mi][ni][j];
;   })
	v_fmac_f32_e32 v200, v148, v64
	v_fmac_f32_e32 v201, v149, v65
	v_fmac_f32_e32 v202, v150, v66
	v_fmac_f32_e32 v203, v151, v67
	v_fmac_f32_e32 v204, v152, v68
	v_fmac_f32_e32 v205, v153, v69
	v_fmac_f32_e32 v206, v154, v70
	v_fmac_f32_e32 v207, v155, v71
	v_fmac_f32_e32 v208, v156, v72
	v_fmac_f32_e32 v209, v157, v73
	v_fmac_f32_e32 v210, v158, v74
	v_fmac_f32_e32 v211, v159, v75
	v_fmac_f32_e32 v212, v160, v76
	v_fmac_f32_e32 v213, v161, v77
	v_fmac_f32_e32 v214, v162, v78
	v_fmac_f32_e32 v215, v163, v79
	v_fmac_f32_e32 v216, v168, v80
	v_fmac_f32_e32 v217, v169, v81
	v_fmac_f32_e32 v218, v170, v82
	v_fmac_f32_e32 v219, v171, v83
	v_fmac_f32_e32 v220, v172, v84
	v_fmac_f32_e32 v221, v173, v85
	v_fmac_f32_e32 v222, v174, v86
	v_fmac_f32_e32 v223, v175, v87
	v_fmac_f32_e32 v228, v176, v88
	v_fmac_f32_e32 v229, v177, v89
	v_fmac_f32_e32 v230, v178, v90
	v_fmac_f32_e32 v231, v179, v91
	v_fmac_f32_e32 v232, v180, v92
	v_fmac_f32_e32 v233, v181, v93
	v_fmac_f32_e32 v234, v182, v94
	v_fmac_f32_e32 v235, v183, v95
	global_store_dwordx4 v248, v[200:203], s[22:23] offset:0
	global_store_dwordx4 v248, v[204:207], s[22:23] offset:64
	global_store_dwordx4 v248, v[208:211], s[22:23] offset:128
	global_store_dwordx4 v248, v[212:215], s[22:23] offset:192
	global_store_dwordx4 v248, v[216:219], s[22:23] offset:256
	global_store_dwordx4 v248, v[220:223], s[22:23] offset:320
	global_store_dwordx4 v248, v[228:231], s[22:23] offset:384
	global_store_dwordx4 v248, v[232:235], s[22:23] offset:448
	s_add_u32 s22, s22, 0x10000
	s_addc_u32 s23, s23, 0
	s_waitcnt vmcnt(0)
	v_fmac_f32_e32 v128, v148, v96
	v_fmac_f32_e32 v129, v149, v97
	v_fmac_f32_e32 v130, v150, v98
	v_fmac_f32_e32 v131, v151, v99
	v_fmac_f32_e32 v132, v152, v100
	v_fmac_f32_e32 v133, v153, v101
	v_fmac_f32_e32 v134, v154, v102
	v_fmac_f32_e32 v135, v155, v103
	v_fmac_f32_e32 v136, v156, v104
	v_fmac_f32_e32 v137, v157, v105
	v_fmac_f32_e32 v138, v158, v106
	v_fmac_f32_e32 v139, v159, v107
	v_fmac_f32_e32 v140, v160, v108
	v_fmac_f32_e32 v141, v161, v109
	v_fmac_f32_e32 v142, v162, v110
	v_fmac_f32_e32 v143, v163, v111
	v_fmac_f32_e32 v184, v168, v112
	v_fmac_f32_e32 v185, v169, v113
	v_fmac_f32_e32 v186, v170, v114
	v_fmac_f32_e32 v187, v171, v115
	v_fmac_f32_e32 v188, v172, v116
	v_fmac_f32_e32 v189, v173, v117
	v_fmac_f32_e32 v190, v174, v118
	v_fmac_f32_e32 v191, v175, v119
	v_fmac_f32_e32 v192, v176, v120
	v_fmac_f32_e32 v193, v177, v121
	v_fmac_f32_e32 v194, v178, v122
	v_fmac_f32_e32 v195, v179, v123
	v_fmac_f32_e32 v196, v180, v124
	v_fmac_f32_e32 v197, v181, v125
	v_fmac_f32_e32 v198, v182, v126
	v_fmac_f32_e32 v199, v183, v127
	global_store_dwordx4 v248, v[128:131], s[22:23] offset:0
	global_store_dwordx4 v248, v[132:135], s[22:23] offset:64
	global_store_dwordx4 v248, v[136:139], s[22:23] offset:128
	global_store_dwordx4 v248, v[140:143], s[22:23] offset:192
	global_store_dwordx4 v248, v[184:187], s[22:23] offset:256
	global_store_dwordx4 v248, v[188:191], s[22:23] offset:320
	global_store_dwordx4 v248, v[192:195], s[22:23] offset:384
	global_store_dwordx4 v248, v[196:199], s[22:23] offset:448
	s_waitcnt vmcnt(0) lgkmcnt(0)
	s_barrier
	s_mov_b64 s[50:51], 0

; __global__ void __launch_bounds__(256, 2) fwd_megakernel(Params p_unused) {
;     ...
;   __shared__ __attribute__((aligned(16))) char smem[SMEM_BYTES];
	.amdhsa_kernel _Z14fwd_megakernel6Params
		.amdhsa_group_segment_fixed_size 73728
		.amdhsa_private_segment_fixed_size 0
		.amdhsa_kernarg_size 808
		.amdhsa_user_sgpr_count 2
		.amdhsa_user_sgpr_dispatch_ptr 0
		.amdhsa_user_sgpr_queue_ptr 0
		.amdhsa_user_sgpr_kernarg_segment_ptr 1
		.amdhsa_user_sgpr_dispatch_id 0
		.amdhsa_user_sgpr_kernarg_preload_length 0
		.amdhsa_user_sgpr_kernarg_preload_offset 0
		.amdhsa_user_sgpr_private_segment_size 0
		.amdhsa_uses_dynamic_stack 0
		.amdhsa_enable_private_segment 0
		.amdhsa_system_sgpr_workgroup_id_x 1
		.amdhsa_system_sgpr_workgroup_id_y 0
		.amdhsa_system_sgpr_workgroup_id_z 0
		.amdhsa_system_sgpr_workgroup_info 0
		.amdhsa_system_vgpr_workitem_id 2
		.amdhsa_next_free_vgpr 256
		.amdhsa_next_free_sgpr 100
		.amdhsa_accum_offset 256
		.amdhsa_reserve_vcc 1
		.amdhsa_float_round_mode_32 0
		.amdhsa_float_round_mode_16_64 0
		.amdhsa_float_denorm_mode_32 3
		.amdhsa_float_denorm_mode_16_64 3
		.amdhsa_dx10_clamp 1
		.amdhsa_ieee_mode 1
		.amdhsa_fp16_overflow 0
		.amdhsa_tg_split 0
		.amdhsa_exception_fp_ieee_invalid_op 0
		.amdhsa_exception_fp_denorm_src 0
		.amdhsa_exception_fp_ieee_div_zero 0
		.amdhsa_exception_fp_ieee_overflow 0
		.amdhsa_exception_fp_ieee_underflow 0
		.amdhsa_exception_fp_ieee_inexact 0
		.amdhsa_exception_int_div_zero 0
	.end_amdhsa_kernel

; __global__ void __launch_bounds__(256, 2) fwd_megakernel(Params p_unused) {
;     ...
;   __shared__ __attribute__((aligned(16))) char smem[SMEM_BYTES];
amdhsa.kernels:
  - .agpr_count:     0
    .args:
      - .offset:         0
        .size:           552
        .value_kind:     by_value
      - .offset:         552
        .size:           4
        .value_kind:     hidden_block_count_x
      - .offset:         556
        .size:           4
        .value_kind:     hidden_block_count_y
      - .offset:         560
        .size:           4
        .value_kind:     hidden_block_count_z
      - .offset:         564
        .size:           2
        .value_kind:     hidden_group_size_x
      - .offset:         566
        .size:           2
        .value_kind:     hidden_group_size_y
      - .offset:         568
        .size:           2
        .value_kind:     hidden_group_size_z
      - .offset:         570
        .size:           2
        .value_kind:     hidden_remainder_x
      - .offset:         572
        .size:           2
        .value_kind:     hidden_remainder_y
      - .offset:         574
        .size:           2
        .value_kind:     hidden_remainder_z
      - .offset:         592
        .size:           8
        .value_kind:     hidden_global_offset_x
      - .offset:         600
        .size:           8
        .value_kind:     hidden_global_offset_y
      - .offset:         608
        .size:           8
        .value_kind:     hidden_global_offset_z
      - .offset:         616
        .size:           2
        .value_kind:     hidden_grid_dims
      - .offset:         640
        .size:           8
        .value_kind:     hidden_multigrid_sync_arg
    .group_segment_fixed_size: 73728
    .kernarg_segment_align: 8
    .kernarg_segment_size: 808
    .language:       OpenCL C
    .language_version:
      - 2
      - 0
    .max_flat_workgroup_size: 256
    .name:           _Z14fwd_megakernel6Params
    .private_segment_fixed_size: 0
    .sgpr_count:     106
    .sgpr_spill_count: 120
    .symbol:         _Z14fwd_megakernel6Params.kd
    .uniform_work_group_size: 1
    .uses_dynamic_stack: false
    .vgpr_count:     256
    .vgpr_spill_count: 0
    .wavefront_size: 64
